# memory-side-cache warm-up: at the out-projection phase entry every thread touches two lines of the bf16 W_up so the up-projection GEMM starts with hot weights (v132 base)
# speedup vs baseline: 1.0149x; 1.0149x over previous
.LBB0_89:
	v_readlane_b32 s0, v255, 16
	s_cmp_lt_i32 s0, 5
	s_mov_b64 s[4:5], -1
	s_cbranch_scc1 .LBB0_171
	v_readlane_b32 s0, v255, 16
	s_cmp_eq_u32 s0, 5
	s_cbranch_scc0 .LBB0_170
	v_lshl_add_u32 v246, s80, 9, v235
	v_lshlrev_b32_e32 v246, 7, v246
	v_add_u32_e32 v248, 0x3400000, v246
	v_add_u32_e32 v246, 0x2400000, v246
	v_mov_b32_e32 v247, 0
	v_mov_b32_e32 v249, 0
	v_lshl_add_u64 v[246:247], s[12:13], 0, v[246:247]
	v_lshl_add_u64 v[248:249], s[12:13], 0, v[248:249]
	global_load_dword v250, v[246:247], off
	global_load_dword v250, v[248:249], off
	s_add_u32 s0, s12, 0x6400000
	s_addc_u32 s1, s13, 0
	s_add_u32 s2, s12, 0x1c00000
	s_addc_u32 s3, s13, 0
	s_add_i32 s4, s94, 8
	s_cmp_gt_u32 s4, 16
	s_mov_b64 s[4:5], -1
	s_cbranch_scc0 .LBB0_131
	s_cmpk_lt_i32 s80, 0x100
	s_cselect_b64 s[18:19], -1, 0
	s_cmpk_gt_i32 s80, 0xff
	v_readfirstlane_b32 s14, v235
	s_cbranch_scc1 .LBB0_98
	s_ashr_i32 s4, s80, 31
	s_lshr_b32 s4, s4, 29
	s_add_i32 s15, s80, s4
	s_and_b32 s4, s15, -8
	s_sub_i32 s21, s80, s4
	s_cmp_gt_i32 s21, -1
	s_mov_b64 s[4:5], -1
	s_cbranch_scc0 .LBB0_95
	s_lshl_b32 s23, s21, 5
	s_mov_b64 s[4:5], 0
